# attention A V-phase: every exp followed by an independent row-sum add / cvt (transcendental pipe overlapped with the main VALU)
# speedup vs baseline: 1.0096x; 1.0022x over previous
; __device__ __forceinline__ void expHalf(f32x16& p0) {
; #pragma unroll
;     for (int r = 0; r < 16; ++r) p0[r] = __builtin_amdgcn_exp2f(p0[r]);
; }
; __device__ __forceinline__ void finishSM(f32x16& p0, f32x16& p1, float& l_reg, bf16x8& pa0, bf16x8& pa1, bf16x8& pa2, bf16x8& pa3) {
;     float ps = 0;
; #pragma unroll
;     for (int r = 0; r < 16; ++r) ps += p0[r];
; #pragma unroll
;     for (int r = 0; r < 16; ++r) ps += p1[r];
;     l_reg += ps;
;     ...
;     PK4(p0, 0, pa0); PK4(p0, 8, pa1); PK4(p1, 0, pa2); PK4(p1, 8, pa3);
.Lat_far_g0l:
	v_exp_f32_e32 v112, v112
	v_exp_f32_e32 v113, v113
	v_exp_f32_e32 v114, v114
	v_add_f32_e32 v64, v64, v112
	v_exp_f32_e32 v115, v115
	v_add_f32_e32 v65, v65, v113
	v_exp_f32_e32 v116, v116
	v_add_f32_e32 v66, v66, v114
	v_exp_f32_e32 v117, v117
	v_add_f32_e32 v67, v67, v115
	v_exp_f32_e32 v118, v118
	v_add_f32_e32 v64, v64, v116
	v_exp_f32_e32 v119, v119
	v_add_f32_e32 v65, v65, v117
	v_exp_f32_e32 v120, v120
	v_add_f32_e32 v66, v66, v118
	v_exp_f32_e32 v121, v121
	v_add_f32_e32 v67, v67, v119
	v_exp_f32_e32 v122, v122
	v_add_f32_e32 v64, v64, v120
	v_exp_f32_e32 v123, v123
	v_add_f32_e32 v65, v65, v121
	v_exp_f32_e32 v124, v124
	v_add_f32_e32 v66, v66, v122
	v_exp_f32_e32 v125, v125
	v_add_f32_e32 v67, v67, v123
	v_exp_f32_e32 v126, v126
	v_add_f32_e32 v64, v64, v124
	v_exp_f32_e32 v127, v127
	v_add_f32_e32 v65, v65, v125
	v_exp_f32_e32 v192, v192
	v_add_f32_e32 v66, v66, v126
	v_cvt_pk_bf16_f32 v208, v112, v113
	v_exp_f32_e32 v193, v193
	v_add_f32_e32 v67, v67, v127
	v_cvt_pk_bf16_f32 v209, v114, v115
	v_exp_f32_e32 v194, v194
	v_add_f32_e32 v64, v64, v192
	v_cvt_pk_bf16_f32 v210, v116, v117
	v_exp_f32_e32 v195, v195
	v_add_f32_e32 v65, v65, v193
	v_cvt_pk_bf16_f32 v211, v118, v119
	v_exp_f32_e32 v196, v196
	v_add_f32_e32 v66, v66, v194
	v_cvt_pk_bf16_f32 v212, v120, v121
	v_exp_f32_e32 v197, v197
	v_add_f32_e32 v67, v67, v195
	v_cvt_pk_bf16_f32 v213, v122, v123
	v_exp_f32_e32 v198, v198
	v_add_f32_e32 v64, v64, v196
	v_cvt_pk_bf16_f32 v214, v124, v125
	v_exp_f32_e32 v199, v199
	v_add_f32_e32 v65, v65, v197
	v_cvt_pk_bf16_f32 v215, v126, v127
	v_exp_f32_e32 v200, v200
	v_add_f32_e32 v66, v66, v198
	v_exp_f32_e32 v201, v201
	v_add_f32_e32 v67, v67, v199
	v_exp_f32_e32 v202, v202
	v_add_f32_e32 v64, v64, v200
	v_exp_f32_e32 v203, v203
	v_add_f32_e32 v65, v65, v201
	v_exp_f32_e32 v204, v204
	v_add_f32_e32 v66, v66, v202
	v_exp_f32_e32 v205, v205
	v_add_f32_e32 v67, v67, v203
	v_exp_f32_e32 v206, v206
	v_add_f32_e32 v64, v64, v204
	v_exp_f32_e32 v207, v207
	v_add_f32_e32 v65, v65, v205
	v_add_f32_e32 v66, v66, v206
	v_add_f32_e32 v67, v67, v207
	v_cvt_pk_bf16_f32 v216, v192, v193
	v_cvt_pk_bf16_f32 v217, v194, v195
	v_cvt_pk_bf16_f32 v218, v196, v197
	v_cvt_pk_bf16_f32 v219, v198, v199
	v_cvt_pk_bf16_f32 v220, v200, v201
	v_cvt_pk_bf16_f32 v221, v202, v203
	v_cvt_pk_bf16_f32 v222, v204, v205
	v_cvt_pk_bf16_f32 v223, v206, v207
	s_add_i32 s99, s23, 64
	s_cmp_ge_i32 s99, s30
	s_cselect_b32 s6, s22, s98
	s_cmp_le_i32 s99, s29
	s_cselect_b32 s6, s21, s6
	s_nop 0
	s_cmp_lg_u32 s6, s9
	s_cbranch_scc0 .Lat_c0same_g0l
	s_mov_b32 s9, s6
	v_mov_b32_e32 v68, s9
	v_mov_b32_e32 v69, s9
	v_mov_b32_e32 v70, s9
	v_mov_b32_e32 v71, s9
	v_mov_b32_e32 v72, s9
	v_mov_b32_e32 v73, s9
	v_mov_b32_e32 v74, s9
	v_mov_b32_e32 v75, s9
	v_mov_b32_e32 v76, s9
	v_mov_b32_e32 v77, s9
	v_mov_b32_e32 v78, s9
	v_mov_b32_e32 v79, s9
	v_mov_b32_e32 v80, s9
	v_mov_b32_e32 v81, s9
	v_mov_b32_e32 v82, s9
	v_mov_b32_e32 v83, s9

; #define SBAR() __builtin_amdgcn_sched_barrier(0)
; #define PVLOAD(D0, X) do { X[0] = tr_read<v_rd_off(D0, 0, 0)>(vb); X[1] = tr_read<v_rd_off(D0, 0, 1)>(vb); X[2] = tr_read<v_rd_off(D0, 1, 0)>(vb); X[3] = tr_read<v_rd_off(D0, 1, 1)>(vb); \
;     X[4] = tr_read<v_rd_off(D0, 2, 0)>(vb); X[5] = tr_read<v_rd_off(D0, 2, 1)>(vb); X[6] = tr_read<v_rd_off(D0, 3, 0)>(vb); X[7] = tr_read<v_rd_off(D0, 3, 1)>(vb); } while (0)
; #define PVMMA(OD, X) do { OD = __builtin_amdgcn_mfma_f32_32x32x16_bf16(pa0, PVPK(X[0], X[1]), OD, 0, 0, 0); OD = __builtin_amdgcn_mfma_f32_32x32x16_bf16(pa1, PVPK(X[2], X[3]), OD, 0, 0, 0); \
;     OD = __builtin_amdgcn_mfma_f32_32x32x16_bf16(pa2, PVPK(X[4], X[5]), OD, 0, 0, 0); OD = __builtin_amdgcn_mfma_f32_32x32x16_bf16(pa3, PVPK(X[6], X[7]), OD, 0, 0, 0); } while (0)
; #define PVWAIT() do { asm volatile("s_waitcnt lgkmcnt(0)" ::: "memory"); SBAR(); } while (0)
; #define PVEXP(P, B, N) do { _Pragma("unroll") for (int r = (B); r < (B) + (N); ++r) P[r] = __builtin_amdgcn_exp2f(P[r]); } while (0)
; __device__ __forceinline__ void expHalf(f32x16& p0) {
; #pragma unroll
;     for (int r = 0; r < 16; ++r) p0[r] = __builtin_amdgcn_exp2f(p0[r]);
; }
; __device__ __forceinline__ void finishSM(f32x16& p0, f32x16& p1, float& l_reg, bf16x8& pa0, bf16x8& pa1, bf16x8& pa2, bf16x8& pa3) {
;     float ps = 0;
; #pragma unroll
;     for (int r = 0; r < 16; ++r) ps += p0[r];
; #pragma unroll
;     for (int r = 0; r < 16; ++r) ps += p1[r];
;     l_reg += ps;
;     ...
;     PK4(p0, 0, pa0); PK4(p0, 8, pa1); PK4(p1, 0, pa2); PK4(p1, 8, pa3);
; template <int NB> __device__ __forceinline__ void pv_blocks(f32x16* o, int vb, bf16x8 pa0, bf16x8 pa1, bf16x8 pa2, bf16x8 pa3, f32x16& pe0, f32x16& pe1) {
;     s16x4 x[8], y[8];
;     ...
;     PVLOAD(0, x); PVWAIT();
;     if (NB == 4) {
;         PVLOAD(1, y); SBAR(); PVMMA(o[0], x); PVEXP(pe0, 0, 8); SBAR(); PVWAIT();
;         PVLOAD(2, x); SBAR(); PVMMA(o[1], y); PVEXP(pe0, 8, 8); SBAR(); PVWAIT();
;         PVLOAD(3, y); SBAR(); PVMMA(o[2], x); PVEXP(pe1, 0, 8); SBAR(); PVWAIT();
;         PVMMA(o[3], y); PVEXP(pe1, 8, 8);
;     } else {
;         PVLOAD(1, y); SBAR(); PVMMA(o[0], x); PVEXP(pe0, 0, 16); SBAR(); PVWAIT();
;         PVMMA(o[1], y); PVEXP(pe1, 0, 16);
;     }
.Lat_far_g0p:
	v_exp_f32_e32 v112, v112
	v_exp_f32_e32 v113, v113
	v_exp_f32_e32 v114, v114
	v_add_f32_e32 v64, v64, v112
	v_exp_f32_e32 v115, v115
	v_add_f32_e32 v65, v65, v113
	v_exp_f32_e32 v116, v116
	v_add_f32_e32 v66, v66, v114
	v_exp_f32_e32 v117, v117
	v_add_f32_e32 v67, v67, v115
	v_exp_f32_e32 v118, v118
	v_add_f32_e32 v64, v64, v116
	v_exp_f32_e32 v119, v119
	v_add_f32_e32 v65, v65, v117
	v_exp_f32_e32 v120, v120
	v_add_f32_e32 v66, v66, v118
	v_exp_f32_e32 v121, v121
	v_add_f32_e32 v67, v67, v119
	v_exp_f32_e32 v122, v122
	v_add_f32_e32 v64, v64, v120
	v_exp_f32_e32 v123, v123
	v_add_f32_e32 v65, v65, v121
	v_exp_f32_e32 v124, v124
	v_add_f32_e32 v66, v66, v122
	v_exp_f32_e32 v125, v125
	v_add_f32_e32 v67, v67, v123
	v_exp_f32_e32 v126, v126
	v_add_f32_e32 v64, v64, v124
	v_exp_f32_e32 v127, v127
	v_add_f32_e32 v65, v65, v125
	v_exp_f32_e32 v192, v192
	v_add_f32_e32 v66, v66, v126
	v_cvt_pk_bf16_f32 v208, v112, v113
	v_exp_f32_e32 v193, v193
	v_add_f32_e32 v67, v67, v127
	v_cvt_pk_bf16_f32 v209, v114, v115
	v_exp_f32_e32 v194, v194
	v_add_f32_e32 v64, v64, v192
	v_cvt_pk_bf16_f32 v210, v116, v117
	v_exp_f32_e32 v195, v195
	v_add_f32_e32 v65, v65, v193
	v_cvt_pk_bf16_f32 v211, v118, v119
	v_exp_f32_e32 v196, v196
	v_add_f32_e32 v66, v66, v194
	v_cvt_pk_bf16_f32 v212, v120, v121
	v_exp_f32_e32 v197, v197
	v_add_f32_e32 v67, v67, v195
	v_cvt_pk_bf16_f32 v213, v122, v123
	v_exp_f32_e32 v198, v198
	v_add_f32_e32 v64, v64, v196
	v_cvt_pk_bf16_f32 v214, v124, v125
	v_exp_f32_e32 v199, v199
	v_add_f32_e32 v65, v65, v197
	v_cvt_pk_bf16_f32 v215, v126, v127
	v_exp_f32_e32 v200, v200
	v_add_f32_e32 v66, v66, v198
	v_exp_f32_e32 v201, v201
	v_add_f32_e32 v67, v67, v199
	v_exp_f32_e32 v202, v202
	v_add_f32_e32 v64, v64, v200
	v_exp_f32_e32 v203, v203
	v_add_f32_e32 v65, v65, v201
	v_exp_f32_e32 v204, v204
	v_add_f32_e32 v66, v66, v202
	v_exp_f32_e32 v205, v205
	v_add_f32_e32 v67, v67, v203
	v_exp_f32_e32 v206, v206
	v_add_f32_e32 v64, v64, v204
	v_exp_f32_e32 v207, v207
	v_add_f32_e32 v65, v65, v205
	v_add_f32_e32 v66, v66, v206
	v_add_f32_e32 v67, v67, v207
	v_cvt_pk_bf16_f32 v216, v192, v193
	v_cvt_pk_bf16_f32 v217, v194, v195
	v_cvt_pk_bf16_f32 v218, v196, v197
	v_cvt_pk_bf16_f32 v219, v198, v199
	v_cvt_pk_bf16_f32 v220, v200, v201
	v_cvt_pk_bf16_f32 v221, v202, v203
	v_cvt_pk_bf16_f32 v222, v204, v205
	v_cvt_pk_bf16_f32 v223, v206, v207
	s_nop 1
	s_waitcnt vmcnt(0)
	s_barrier
	s_setprio 0
	ds_read_b64_tr_b16 v[84:85], v168 offset:0
	ds_read_b64_tr_b16 v[86:87], v168 offset:2048
	ds_read_b64_tr_b16 v[88:89], v168 offset:4096
	ds_read_b64_tr_b16 v[90:91], v168 offset:6144
	ds_read_b64_tr_b16 v[92:93], v168 offset:8192
	ds_read_b64_tr_b16 v[94:95], v168 offset:10240
	ds_read_b64_tr_b16 v[128:129], v168 offset:12288
	ds_read_b64_tr_b16 v[130:131], v168 offset:14336
	ds_read_b64_tr_b16 v[132:133], v168 offset:512
	ds_read_b64_tr_b16 v[134:135], v168 offset:2560
	ds_read_b64_tr_b16 v[140:141], v168 offset:4608
	ds_read_b64_tr_b16 v[142:143], v168 offset:6656
	ds_read_b64_tr_b16 v[152:153], v168 offset:8704
	ds_read_b64_tr_b16 v[154:155], v168 offset:10752
	s_waitcnt lgkmcnt(12)
	v_mfma_f32_32x32x16_bf16 v[0:15], v[208:211], v[84:87], v[0:15]
	ds_read_b64_tr_b16 v[160:161], v168 offset:12800
	ds_read_b64_tr_b16 v[162:163], v168 offset:14848
	s_waitcnt lgkmcnt(12)
	v_mfma_f32_32x32x16_bf16 v[0:15], v[212:215], v[88:91], v[0:15]
	ds_read_b64_tr_b16 v[84:85], v168 offset:1024
	ds_read_b64_tr_b16 v[86:87], v168 offset:3072
	s_waitcnt lgkmcnt(12)
	v_mfma_f32_32x32x16_bf16 v[0:15], v[216:219], v[92:95], v[0:15]
	ds_read_b64_tr_b16 v[88:89], v168 offset:5120
	ds_read_b64_tr_b16 v[90:91], v168 offset:7168
	s_waitcnt lgkmcnt(12)
	v_mfma_f32_32x32x16_bf16 v[0:15], v[220:223], v[128:131], v[0:15]
	ds_read_b64_tr_b16 v[92:93], v168 offset:9216
	ds_read_b64_tr_b16 v[94:95], v168 offset:11264
	s_waitcnt lgkmcnt(12)
	v_mfma_f32_32x32x16_bf16 v[16:31], v[208:211], v[132:135], v[16:31]
	ds_read_b64_tr_b16 v[128:129], v168 offset:13312
	ds_read_b64_tr_b16 v[130:131], v168 offset:15360
	s_waitcnt lgkmcnt(12)
	v_mfma_f32_32x32x16_bf16 v[16:31], v[212:215], v[140:143], v[16:31]
	ds_read_b64_tr_b16 v[132:133], v168 offset:1536
	ds_read_b64_tr_b16 v[134:135], v168 offset:3584
	s_waitcnt lgkmcnt(12)
	v_mfma_f32_32x32x16_bf16 v[16:31], v[216:219], v[152:155], v[16:31]
	ds_read_b64_tr_b16 v[140:141], v168 offset:5632
	ds_read_b64_tr_b16 v[142:143], v168 offset:7680
	s_waitcnt lgkmcnt(12)
	v_mfma_f32_32x32x16_bf16 v[16:31], v[220:223], v[160:163], v[16:31]
	ds_read_b64_tr_b16 v[152:153], v168 offset:9728
	ds_read_b64_tr_b16 v[154:155], v168 offset:11776
	s_waitcnt lgkmcnt(12)
	v_mfma_f32_32x32x16_bf16 v[32:47], v[208:211], v[84:87], v[32:47]
	ds_read_b64_tr_b16 v[160:161], v168 offset:13824
	ds_read_b64_tr_b16 v[162:163], v168 offset:15872
	v_xor_b32_e32 v168, 0x4000, v168
	s_waitcnt lgkmcnt(12)
	v_mfma_f32_32x32x16_bf16 v[32:47], v[212:215], v[88:91], v[32:47]
	s_waitcnt lgkmcnt(10)
	v_mfma_f32_32x32x16_bf16 v[32:47], v[216:219], v[92:95], v[32:47]
	s_waitcnt lgkmcnt(8)
	v_mfma_f32_32x32x16_bf16 v[32:47], v[220:223], v[128:131], v[32:47]
	s_waitcnt lgkmcnt(6)
	v_mfma_f32_32x32x16_bf16 v[48:63], v[208:211], v[132:135], v[48:63]
	s_waitcnt lgkmcnt(4)
	v_mfma_f32_32x32x16_bf16 v[48:63], v[212:215], v[140:143], v[48:63]
	s_waitcnt lgkmcnt(2)
	v_mfma_f32_32x32x16_bf16 v[48:63], v[216:219], v[152:155], v[48:63]
	s_waitcnt lgkmcnt(0)
	v_mfma_f32_32x32x16_bf16 v[48:63], v[220:223], v[160:163], v[48:63]
	s_barrier
	s_barrier
	s_branch .Lat_done

; __device__ __forceinline__ void expHalf(f32x16& p0) {
; #pragma unroll
;     for (int r = 0; r < 16; ++r) p0[r] = __builtin_amdgcn_exp2f(p0[r]);
; }
; __device__ __forceinline__ void finishSM(f32x16& p0, f32x16& p1, float& l_reg, bf16x8& pa0, bf16x8& pa1, bf16x8& pa2, bf16x8& pa3) {
;     float ps = 0;
; #pragma unroll
;     for (int r = 0; r < 16; ++r) ps += p0[r];
; #pragma unroll
;     for (int r = 0; r < 16; ++r) ps += p1[r];
;     l_reg += ps;
;     ...
;     PK4(p0, 0, pa0); PK4(p0, 8, pa1); PK4(p1, 0, pa2); PK4(p1, 8, pa3);
.Lat_far_g1l:
	s_mov_b32 m0, s33
	s_add_u32 s7, s33, 0x2000
	global_load_lds_dwordx4 v171, s[26:27]
	v_exp_f32_e32 v112, v112
	v_exp_f32_e32 v113, v113
	v_exp_f32_e32 v114, v114
	v_add_f32_e32 v64, v64, v112
	v_exp_f32_e32 v115, v115
	v_add_f32_e32 v65, v65, v113
	v_exp_f32_e32 v116, v116
	v_add_f32_e32 v66, v66, v114
	v_exp_f32_e32 v117, v117
	v_add_f32_e32 v67, v67, v115
	v_exp_f32_e32 v118, v118
	v_add_f32_e32 v64, v64, v116
	v_exp_f32_e32 v119, v119
	v_add_f32_e32 v65, v65, v117
	s_mov_b32 m0, s7
	s_xor_b32 s33, s33, 0x4000
	global_load_lds_dwordx4 v172, s[26:27]
	s_add_u32 s26, s26, 0x50000
	s_addc_u32 s27, s27, 0
	v_exp_f32_e32 v120, v120
	v_add_f32_e32 v66, v66, v118
	v_exp_f32_e32 v121, v121
	v_add_f32_e32 v67, v67, v119
	v_exp_f32_e32 v122, v122
	v_add_f32_e32 v64, v64, v120
	v_exp_f32_e32 v123, v123
	v_add_f32_e32 v65, v65, v121
	v_exp_f32_e32 v124, v124
	v_add_f32_e32 v66, v66, v122
	v_exp_f32_e32 v125, v125
	v_add_f32_e32 v67, v67, v123
	v_exp_f32_e32 v126, v126
	v_add_f32_e32 v64, v64, v124
	v_exp_f32_e32 v127, v127
	v_add_f32_e32 v65, v65, v125
	s_mov_b32 m0, s31
	s_add_u32 s7, s31, 0x2000
	global_load_lds_dwordx4 v169, s[24:25]
	v_exp_f32_e32 v192, v192
	v_add_f32_e32 v66, v66, v126
	v_cvt_pk_bf16_f32 v208, v112, v113
	v_exp_f32_e32 v193, v193
	v_add_f32_e32 v67, v67, v127
	v_cvt_pk_bf16_f32 v209, v114, v115
	v_exp_f32_e32 v194, v194
	v_add_f32_e32 v64, v64, v192
	v_cvt_pk_bf16_f32 v210, v116, v117
	v_exp_f32_e32 v195, v195
	v_add_f32_e32 v65, v65, v193
	v_cvt_pk_bf16_f32 v211, v118, v119
	v_exp_f32_e32 v196, v196
	v_add_f32_e32 v66, v66, v194
	v_cvt_pk_bf16_f32 v212, v120, v121
	v_exp_f32_e32 v197, v197
	v_add_f32_e32 v67, v67, v195
	v_cvt_pk_bf16_f32 v213, v122, v123
	s_mov_b32 m0, s7
	s_add_u32 s31, s31, s100
	global_load_lds_dwordx4 v170, s[24:25]
	s_add_u32 s24, s24, 0x50000
	s_addc_u32 s25, s25, 0
	v_exp_f32_e32 v198, v198
	v_add_f32_e32 v64, v64, v196
	v_cvt_pk_bf16_f32 v214, v124, v125
	v_exp_f32_e32 v199, v199
	v_add_f32_e32 v65, v65, v197
	v_cvt_pk_bf16_f32 v215, v126, v127
	v_exp_f32_e32 v200, v200
	v_add_f32_e32 v66, v66, v198
	v_exp_f32_e32 v201, v201
	v_add_f32_e32 v67, v67, v199
	v_exp_f32_e32 v202, v202
	v_add_f32_e32 v64, v64, v200
	v_exp_f32_e32 v203, v203
	v_add_f32_e32 v65, v65, v201
	v_exp_f32_e32 v204, v204
	v_add_f32_e32 v66, v66, v202
	v_exp_f32_e32 v205, v205
	v_add_f32_e32 v67, v67, v203
	v_exp_f32_e32 v206, v206
	v_add_f32_e32 v64, v64, v204
	v_exp_f32_e32 v207, v207
	v_add_f32_e32 v65, v65, v205
	v_add_f32_e32 v66, v66, v206
	v_add_f32_e32 v67, v67, v207
	v_cvt_pk_bf16_f32 v216, v192, v193
	v_cvt_pk_bf16_f32 v217, v194, v195
	v_cvt_pk_bf16_f32 v218, v196, v197
	v_cvt_pk_bf16_f32 v219, v198, v199
	v_cvt_pk_bf16_f32 v220, v200, v201
	v_cvt_pk_bf16_f32 v221, v202, v203
	v_cvt_pk_bf16_f32 v222, v204, v205
	v_cvt_pk_bf16_f32 v223, v206, v207
	s_add_i32 s99, s23, 64
	s_cmp_ge_i32 s99, s30
	s_cselect_b32 s6, s22, s98
	s_cmp_le_i32 s99, s29
	s_cselect_b32 s6, s21, s6
	s_nop 0
	s_cmp_lg_u32 s6, s9
	s_cbranch_scc0 .Lat_c0same_g1l
	s_mov_b32 s9, s6
	v_mov_b32_e32 v68, s9
	v_mov_b32_e32 v69, s9
	v_mov_b32_e32 v70, s9
	v_mov_b32_e32 v71, s9
	v_mov_b32_e32 v72, s9
	v_mov_b32_e32 v73, s9
	v_mov_b32_e32 v74, s9
	v_mov_b32_e32 v75, s9
	v_mov_b32_e32 v76, s9
	v_mov_b32_e32 v77, s9
	v_mov_b32_e32 v78, s9
	v_mov_b32_e32 v79, s9
	v_mov_b32_e32 v80, s9
	v_mov_b32_e32 v81, s9
	v_mov_b32_e32 v82, s9
	v_mov_b32_e32 v83, s9

; #define SBAR() __builtin_amdgcn_sched_barrier(0)
; #define PVLOAD(D0, X) do { X[0] = tr_read<v_rd_off(D0, 0, 0)>(vb); X[1] = tr_read<v_rd_off(D0, 0, 1)>(vb); X[2] = tr_read<v_rd_off(D0, 1, 0)>(vb); X[3] = tr_read<v_rd_off(D0, 1, 1)>(vb); \
;     X[4] = tr_read<v_rd_off(D0, 2, 0)>(vb); X[5] = tr_read<v_rd_off(D0, 2, 1)>(vb); X[6] = tr_read<v_rd_off(D0, 3, 0)>(vb); X[7] = tr_read<v_rd_off(D0, 3, 1)>(vb); } while (0)
; #define PVMMA(OD, X) do { OD = __builtin_amdgcn_mfma_f32_32x32x16_bf16(pa0, PVPK(X[0], X[1]), OD, 0, 0, 0); OD = __builtin_amdgcn_mfma_f32_32x32x16_bf16(pa1, PVPK(X[2], X[3]), OD, 0, 0, 0); \
;     OD = __builtin_amdgcn_mfma_f32_32x32x16_bf16(pa2, PVPK(X[4], X[5]), OD, 0, 0, 0); OD = __builtin_amdgcn_mfma_f32_32x32x16_bf16(pa3, PVPK(X[6], X[7]), OD, 0, 0, 0); } while (0)
; #define PVWAIT() do { asm volatile("s_waitcnt lgkmcnt(0)" ::: "memory"); SBAR(); } while (0)
; #define PVEXP(P, B, N) do { _Pragma("unroll") for (int r = (B); r < (B) + (N); ++r) P[r] = __builtin_amdgcn_exp2f(P[r]); } while (0)
; __device__ __forceinline__ void expHalf(f32x16& p0) {
; #pragma unroll
;     for (int r = 0; r < 16; ++r) p0[r] = __builtin_amdgcn_exp2f(p0[r]);
; }
; __device__ __forceinline__ void finishSM(f32x16& p0, f32x16& p1, float& l_reg, bf16x8& pa0, bf16x8& pa1, bf16x8& pa2, bf16x8& pa3) {
;     float ps = 0;
; #pragma unroll
;     for (int r = 0; r < 16; ++r) ps += p0[r];
; #pragma unroll
;     for (int r = 0; r < 16; ++r) ps += p1[r];
;     l_reg += ps;
;     ...
;     PK4(p0, 0, pa0); PK4(p0, 8, pa1); PK4(p1, 0, pa2); PK4(p1, 8, pa3);
; template <int NB> __device__ __forceinline__ void pv_blocks(f32x16* o, int vb, bf16x8 pa0, bf16x8 pa1, bf16x8 pa2, bf16x8 pa3, f32x16& pe0, f32x16& pe1) {
;     s16x4 x[8], y[8];
;     ...
;     PVLOAD(0, x); PVWAIT();
;     if (NB == 4) {
;         PVLOAD(1, y); SBAR(); PVMMA(o[0], x); PVEXP(pe0, 0, 8); SBAR(); PVWAIT();
;         PVLOAD(2, x); SBAR(); PVMMA(o[1], y); PVEXP(pe0, 8, 8); SBAR(); PVWAIT();
;         PVLOAD(3, y); SBAR(); PVMMA(o[2], x); PVEXP(pe1, 0, 8); SBAR(); PVWAIT();
;         PVMMA(o[3], y); PVEXP(pe1, 8, 8);
;     } else {
;         PVLOAD(1, y); SBAR(); PVMMA(o[0], x); PVEXP(pe0, 0, 16); SBAR(); PVWAIT();
;         PVMMA(o[1], y); PVEXP(pe1, 0, 16);
;     }
.Lat_far_g1p:
	v_exp_f32_e32 v112, v112
	v_exp_f32_e32 v113, v113
	v_exp_f32_e32 v114, v114
	v_add_f32_e32 v64, v64, v112
	v_exp_f32_e32 v115, v115
	v_add_f32_e32 v65, v65, v113
	v_exp_f32_e32 v116, v116
	v_add_f32_e32 v66, v66, v114
	v_exp_f32_e32 v117, v117
	v_add_f32_e32 v67, v67, v115
	v_exp_f32_e32 v118, v118
	v_add_f32_e32 v64, v64, v116
	v_exp_f32_e32 v119, v119
	v_add_f32_e32 v65, v65, v117
	v_exp_f32_e32 v120, v120
	v_add_f32_e32 v66, v66, v118
	v_exp_f32_e32 v121, v121
	v_add_f32_e32 v67, v67, v119
	v_exp_f32_e32 v122, v122
	v_add_f32_e32 v64, v64, v120
	v_exp_f32_e32 v123, v123
	v_add_f32_e32 v65, v65, v121
	v_exp_f32_e32 v124, v124
	v_add_f32_e32 v66, v66, v122
	v_exp_f32_e32 v125, v125
	v_add_f32_e32 v67, v67, v123
	v_exp_f32_e32 v126, v126
	v_add_f32_e32 v64, v64, v124
	v_exp_f32_e32 v127, v127
	v_add_f32_e32 v65, v65, v125
	v_exp_f32_e32 v192, v192
	v_add_f32_e32 v66, v66, v126
	v_cvt_pk_bf16_f32 v208, v112, v113
	v_exp_f32_e32 v193, v193
	v_add_f32_e32 v67, v67, v127
	v_cvt_pk_bf16_f32 v209, v114, v115
	v_exp_f32_e32 v194, v194
	v_add_f32_e32 v64, v64, v192
	v_cvt_pk_bf16_f32 v210, v116, v117
	v_exp_f32_e32 v195, v195
	v_add_f32_e32 v65, v65, v193
	v_cvt_pk_bf16_f32 v211, v118, v119
	v_exp_f32_e32 v196, v196
	v_add_f32_e32 v66, v66, v194
	v_cvt_pk_bf16_f32 v212, v120, v121
	v_exp_f32_e32 v197, v197
	v_add_f32_e32 v67, v67, v195
	v_cvt_pk_bf16_f32 v213, v122, v123
	v_exp_f32_e32 v198, v198
	v_add_f32_e32 v64, v64, v196
	v_cvt_pk_bf16_f32 v214, v124, v125
	v_exp_f32_e32 v199, v199
	v_add_f32_e32 v65, v65, v197
	v_cvt_pk_bf16_f32 v215, v126, v127
	v_exp_f32_e32 v200, v200
	v_add_f32_e32 v66, v66, v198
	v_exp_f32_e32 v201, v201
	v_add_f32_e32 v67, v67, v199
	v_exp_f32_e32 v202, v202
	v_add_f32_e32 v64, v64, v200
	v_exp_f32_e32 v203, v203
	v_add_f32_e32 v65, v65, v201
	v_exp_f32_e32 v204, v204
	v_add_f32_e32 v66, v66, v202
	v_exp_f32_e32 v205, v205
	v_add_f32_e32 v67, v67, v203
	v_exp_f32_e32 v206, v206
	v_add_f32_e32 v64, v64, v204
	v_exp_f32_e32 v207, v207
	v_add_f32_e32 v65, v65, v205
	v_add_f32_e32 v66, v66, v206
	v_add_f32_e32 v67, v67, v207
	v_cvt_pk_bf16_f32 v216, v192, v193
	v_cvt_pk_bf16_f32 v217, v194, v195
	v_cvt_pk_bf16_f32 v218, v196, v197
	v_cvt_pk_bf16_f32 v219, v198, v199
	v_cvt_pk_bf16_f32 v220, v200, v201
	v_cvt_pk_bf16_f32 v221, v202, v203
	v_cvt_pk_bf16_f32 v222, v204, v205
	v_cvt_pk_bf16_f32 v223, v206, v207
	s_nop 1
	s_waitcnt vmcnt(0)
	s_barrier
	s_setprio 0
	ds_read_b64_tr_b16 v[84:85], v168 offset:0
	ds_read_b64_tr_b16 v[86:87], v168 offset:2048
	ds_read_b64_tr_b16 v[88:89], v168 offset:4096
	ds_read_b64_tr_b16 v[90:91], v168 offset:6144
	ds_read_b64_tr_b16 v[92:93], v168 offset:8192
	ds_read_b64_tr_b16 v[94:95], v168 offset:10240
	ds_read_b64_tr_b16 v[128:129], v168 offset:12288
	ds_read_b64_tr_b16 v[130:131], v168 offset:14336
	ds_read_b64_tr_b16 v[132:133], v168 offset:512
	ds_read_b64_tr_b16 v[134:135], v168 offset:2560
	ds_read_b64_tr_b16 v[140:141], v168 offset:4608
	ds_read_b64_tr_b16 v[142:143], v168 offset:6656
	ds_read_b64_tr_b16 v[152:153], v168 offset:8704
	ds_read_b64_tr_b16 v[154:155], v168 offset:10752
	s_waitcnt lgkmcnt(12)
	v_mfma_f32_32x32x16_bf16 v[0:15], v[208:211], v[84:87], v[0:15]
	ds_read_b64_tr_b16 v[160:161], v168 offset:12800
	ds_read_b64_tr_b16 v[162:163], v168 offset:14848
	s_waitcnt lgkmcnt(12)
	v_mfma_f32_32x32x16_bf16 v[0:15], v[212:215], v[88:91], v[0:15]
	ds_read_b64_tr_b16 v[84:85], v168 offset:1024
	ds_read_b64_tr_b16 v[86:87], v168 offset:3072
	s_waitcnt lgkmcnt(12)
	v_mfma_f32_32x32x16_bf16 v[0:15], v[216:219], v[92:95], v[0:15]
	ds_read_b64_tr_b16 v[88:89], v168 offset:5120
	ds_read_b64_tr_b16 v[90:91], v168 offset:7168
	s_waitcnt lgkmcnt(12)
	v_mfma_f32_32x32x16_bf16 v[0:15], v[220:223], v[128:131], v[0:15]
	ds_read_b64_tr_b16 v[92:93], v168 offset:9216
	ds_read_b64_tr_b16 v[94:95], v168 offset:11264
	s_waitcnt lgkmcnt(12)
	v_mfma_f32_32x32x16_bf16 v[16:31], v[208:211], v[132:135], v[16:31]
	ds_read_b64_tr_b16 v[128:129], v168 offset:13312
	ds_read_b64_tr_b16 v[130:131], v168 offset:15360
	s_waitcnt lgkmcnt(12)
	v_mfma_f32_32x32x16_bf16 v[16:31], v[212:215], v[140:143], v[16:31]
	ds_read_b64_tr_b16 v[132:133], v168 offset:1536
	ds_read_b64_tr_b16 v[134:135], v168 offset:3584
	s_waitcnt lgkmcnt(12)
	v_mfma_f32_32x32x16_bf16 v[16:31], v[216:219], v[152:155], v[16:31]
	ds_read_b64_tr_b16 v[140:141], v168 offset:5632
	ds_read_b64_tr_b16 v[142:143], v168 offset:7680
	s_waitcnt lgkmcnt(12)
	v_mfma_f32_32x32x16_bf16 v[16:31], v[220:223], v[160:163], v[16:31]
	ds_read_b64_tr_b16 v[152:153], v168 offset:9728
	ds_read_b64_tr_b16 v[154:155], v168 offset:11776
	s_waitcnt lgkmcnt(12)
	v_mfma_f32_32x32x16_bf16 v[32:47], v[208:211], v[84:87], v[32:47]
	ds_read_b64_tr_b16 v[160:161], v168 offset:13824
	ds_read_b64_tr_b16 v[162:163], v168 offset:15872
	v_xor_b32_e32 v168, 0x4000, v168
	s_waitcnt lgkmcnt(12)
	v_mfma_f32_32x32x16_bf16 v[32:47], v[212:215], v[88:91], v[32:47]
	s_waitcnt lgkmcnt(10)
	v_mfma_f32_32x32x16_bf16 v[32:47], v[216:219], v[92:95], v[32:47]
	s_waitcnt lgkmcnt(8)
	v_mfma_f32_32x32x16_bf16 v[32:47], v[220:223], v[128:131], v[32:47]
	s_waitcnt lgkmcnt(6)
	v_mfma_f32_32x32x16_bf16 v[48:63], v[208:211], v[132:135], v[48:63]
	s_waitcnt lgkmcnt(4)
	v_mfma_f32_32x32x16_bf16 v[48:63], v[212:215], v[140:143], v[48:63]
	s_waitcnt lgkmcnt(2)
	v_mfma_f32_32x32x16_bf16 v[48:63], v[216:219], v[152:155], v[48:63]
	s_waitcnt lgkmcnt(0)
	v_mfma_f32_32x32x16_bf16 v[48:63], v[220:223], v[160:163], v[48:63]
	s_waitcnt vmcnt(0)
	s_barrier
